# attention: one lgkmcnt wait per QK MFMA pair, single SGPR base advance per two tiles (per-lane row offsets precomputed)
# baseline (speedup 1.0000x reference)
; __device__ __forceinline__ int lane_id_asm() { int l; asm volatile("v_mbcnt_lo_u32_b32 %0, -1, 0\n\tv_mbcnt_hi_u32_b32 %0, -1, %0" : "=v"(l)); return l; }
; __device__ __forceinline__ int v_st(int k, int c) { const int kk = (k & ~0xC) | ((k & 4) << 1) | ((k & 8) >> 1); return ((kk >> 3) * 4 + (c >> 5)) * 512 + ((kk & 7) * 32 + (c & 31)) * 2; }
; __device__ __forceinline__ int v_rd_base(int lane) { return ((lane & 3) << 3) | (((lane >> 2) & 3) << 6) | (((lane >> 4) & 1) << 5) | (((lane >> 5) & 1) << 8); }
; #define SLOAD(i, k0) do { sr_[i].vs0 = St::ld8(&Vh[(long)((k0) + sr) * LDK + sc]); sr_[i].vs1 = St::ld8(&Vh[(long)((k0) + 32 + sr) * LDK + sc]); \
;     sr_[i].ks0 = St::ld8(&Kh[(long)((k0) + sr) * LDK + sc]); sr_[i].ks1 = St::ld8(&Kh[(long)((k0) + 32 + sr) * LDK + sc]); } while (0)
; template <typename TQ>
; __device__ __forceinline__ void attn_dense_body(const TQ* __restrict__ Qb, const bf16* __restrict__ Kh, const bf16* __restrict__ Vh,
;                                                 unsigned short* __restrict__ Ob, int seq, char* lds, const int wave_s) {
;     ...
;   const int lane = lane_id_asm(), wid = wave_s, tid = wave_s * 64 + lane, r32 = lane & 31, hi = lane >> 5;
;   bf16* V_lds = (bf16*)lds; bf16* K_lds = (bf16*)(lds + 2 * SHM_V);
;   float* ws = (float*)(lds + 2 * SHM_V + 2 * SHM_K) + wid * 64; float* li_l = ws; float* al_l = ws + 32;
;   float m_reg = -1e30f, l_reg = 0; f32x16 o[4] = {}; bf16x8 qr[8];
;   const TQ* Qw = Qb + (long)(wid * QBLK + r32) * LDQ + hi * 8;
; #pragma unroll
;   for (int d0 = 0; d0 < 8; ++d0) qr[d0] = SQ::tobf(SQ::ld8(Qw + d0 * 16));
;   const int sr = tid >> 4, sc = (tid & 15) * 8, vst0 = v_st(sr, sc), vst1 = v_st(32 + sr, sc);
;   const int vb0 = (int)(uintptr_t)V_lds + v_rd_base(lane);
;   struct { typename St::T vs0, vs1, ks0, ks1; } sr_[SDEPTH];
;     ...
;   f32x16 pA0, pA1, pB0, pB1; float mnA, mnB, alA, alB; bf16x8 pa0, pa1, pa2, pa3; const int NT = seq / KVBLK;
;   constexpr int SE = 0, SO = SDEPTH - 1;
;   SLOAD(SE, 0); asm volatile("s_waitcnt vmcnt(0)" ::: "memory"); SWRITE(0, SE); __syncthreads();
;   qkt(pA0, pA1, K_lds, qr, r32, hi); partialSM(pA0, pA1, m_reg, mnA, alA);
.LBB0_574:
	s_mul_i32 s39, s2, 0xc00
	s_mul_hi_u32 s38, s2, 0xc00
	s_add_u32 s45, s6, s39
	s_addc_u32 s47, s7, s38
	s_lshl_b32 s38, s42, 7
	s_ashr_i32 s39, s38, 31
	s_lshl_b64 s[42:43], s[38:39], 1
	s_add_u32 s46, s45, s42
	s_addc_u32 s47, s47, s43
	s_lshl_b64 s[38:39], s[40:41], 1
	s_add_u32 s50, s6, s38
	s_addc_u32 s51, s7, s39
	s_lshl_b32 s44, s44, 7
	s_ashr_i32 s45, s44, 31
	s_lshl_b64 s[38:39], s[44:45], 1
	s_add_u32 s38, s50, s38
	v_readlane_b32 s50, v255, 42
	v_mbcnt_lo_u32_b32 v68, -1, 0
	v_mbcnt_hi_u32_b32 v68, -1, v68
	s_addc_u32 s39, s51, s39
	v_lshlrev_b32_e32 v64, 3, v68
	v_add_u32_e32 v20, s50, v68
	v_ashrrev_i32_e32 v69, 4, v20
	v_add_u32_e32 v21, 32, v69
	v_and_b32_e32 v70, 0x78, v64
	v_mad_i64_i32 v[0:1], s[50:51], v69, s97, 0
	v_mad_i64_i32 v[4:5], s[50:51], v21, s97, 0
	v_or_b32_e32 v0, v0, v70
	v_or_b32_e32 v4, v4, v70
	v_lshl_add_u64 v[8:9], v[0:1], 1, s[38:39]
	v_lshl_add_u64 v[12:13], v[4:5], 1, s[38:39]
	global_load_dwordx4 v[0:3], v[8:9], off offset:2560
	global_load_dwordx4 v[4:7], v[12:13], off offset:2560
	s_nop 0
	global_load_dwordx4 v[8:11], v[8:9], off offset:2048
	s_nop 0
	global_load_dwordx4 v[12:15], v[12:13], off offset:2048
	v_and_b32_e32 v178, 31, v68
	v_readlane_b32 s50, v255, 43
	v_ashrrev_i32_e32 v179, 5, v68
	v_mov_b64_e32 v[16:17], s[46:47]
	v_or_b32_e32 v18, s50, v178
	v_mad_i64_i32 v[16:17], s[46:47], v18, s33, v[16:17]
	v_lshlrev_b32_e32 v18, 3, v179
	v_ashrrev_i32_e32 v19, 31, v18
	v_lshl_add_u64 v[16:17], v[18:19], 1, v[16:17]
	global_load_dwordx4 v[112:115], v[16:17], off
	global_load_dwordx4 v[108:111], v[16:17], off offset:32
	global_load_dwordx4 v[120:123], v[16:17], off offset:64
	global_load_dwordx4 v[124:127], v[16:17], off offset:96
	global_load_dwordx4 v[116:119], v[16:17], off offset:128
	global_load_dwordx4 v[104:107], v[16:17], off offset:160
	global_load_dwordx4 v[100:103], v[16:17], off offset:192
	global_load_dwordx4 v[96:99], v[16:17], off offset:224
	v_and_b32_e32 v19, 0x70, v20
	v_and_b32_e32 v20, 0xfffff0, v69
	v_lshlrev_b32_e32 v22, 1, v69
	v_lshrrev_b32_e32 v23, 1, v69
	v_and_b32_e32 v24, 3, v69
	v_and_or_b32 v20, v69, 8, v20
	v_and_or_b32 v22, v69, 4, v24
	v_and_b32_e32 v24, 0xfffff0, v21
	v_lshlrev_b32_e32 v28, 1, v21
	v_bfe_u32 v18, v64, 5, 2
	v_lshlrev_b32_e32 v25, 1, v70
	v_lshlrev_b32_e32 v26, 8, v69
	v_lshlrev_b32_e32 v21, 8, v21
	v_lshrrev_b32_e32 v20, 1, v20
	v_and_or_b32 v24, v69, 8, v24
	v_lshlrev_b32_e32 v48, 4, v68
	v_bitop3_b32 v26, v25, v26, v19 bitop3:0xde
	v_bitop3_b32 v19, v21, v25, v19 bitop3:0xf6
	v_or_b32_e32 v20, v20, v18
	v_lshrrev_b32_e32 v21, 1, v24
	v_lshlrev_b32_e32 v180, 4, v179
	v_lshlrev_b32_e32 v65, 8, v178
	v_and_b32_e32 v66, 0x70, v48
	v_and_b32_e32 v23, 48, v25
	v_lshlrev_b32_e32 v22, 6, v22
	v_add_u32_e32 v186, 0x8000, v19
	v_lshlrev_b32_e32 v19, 9, v20
	v_or_b32_e32 v18, v21, v18
	v_xad_u32 v27, v66, v180, v65
	v_or3_b32 v19, v19, v22, v23
	v_lshlrev_b32_e32 v18, 9, v18
	v_or3_b32 v18, v18, v22, v23
	v_add_u32_e32 v187, 0, v19
	v_add_u32_e32 v189, 0x8000, v27
	v_add_u32_e32 v185, 0x8000, v26
	v_add_u32_e32 v188, 0, v18
	s_waitcnt vmcnt(0)
	v_readlane_b32 s51, v255, 44
	s_cmp_lg_u32 0, -1
	s_cselect_b32 s51, 0, 0
	s_mov_b32 s81, s80
	s_mov_b32 s82, s80
	s_mov_b32 s83, s80
	s_mov_b32 s84, s80
	s_mov_b32 s85, s80
	s_mov_b32 s86, s80
	s_mov_b32 s87, s80
	s_mov_b32 s88, s80
	s_mov_b32 s89, s80
	s_mov_b32 s90, s80
	s_waitcnt vmcnt(11)
	ds_write_b128 v187, v[0:3]
	s_waitcnt vmcnt(10)
	ds_write_b128 v187, v[4:7] offset:8192
	s_waitcnt vmcnt(9)
	ds_write_b128 v185, v[8:11] offset:32768
	s_waitcnt vmcnt(8)
	ds_write_b128 v185, v[12:15] offset:40960
	s_waitcnt lgkmcnt(0)
	s_barrier
	ds_read_b128 v[0:3], v189 offset:32768
	ds_read_b128 v[4:7], v189 offset:40960
	s_waitcnt vmcnt(7) lgkmcnt(1)
	v_mfma_f32_32x32x16_bf16 v[16:31], v[0:3], v[112:115], 0
	v_add_u32_e32 v0, 32, v180
	v_xad_u32 v0, v0, v66, v65
	v_add_u32_e32 v199, 0x8000, v0
	v_add_u32_e32 v8, 0xc0, v180
	v_xad_u32 v12, v8, v66, v65
	v_add_u32_e32 v201, 0x8000, v12
	v_lshlrev_b32_e32 v10, 1, v68
	s_waitcnt lgkmcnt(0)
	v_mfma_f32_32x32x16_bf16 v[32:47], v[4:7], v[112:115], 0
	ds_read_b128 v[0:3], v199 offset:32768
	ds_read_b128 v[4:7], v199 offset:40960
	s_mov_b32 s91, s80
	s_mov_b32 s92, s80
	s_mov_b32 s93, s80
	s_mov_b32 s94, s80
	s_mov_b32 s95, s80
	s_mov_b32 s50, 2
	s_waitcnt vmcnt(6) lgkmcnt(1)
	v_mfma_f32_32x32x16_bf16 v[16:31], v[0:3], v[108:111], v[16:31]
	v_add_u32_e32 v0, 64, v180
	v_xad_u32 v0, v0, v66, v65
	v_add_u32_e32 v192, 0x8000, v0
	v_lshl_add_u32 v181, v178, 2, s1
	v_mov_b32_e32 v182, 0
	s_waitcnt lgkmcnt(0)
	v_mfma_f32_32x32x16_bf16 v[32:47], v[4:7], v[108:111], v[32:47]
	ds_read_b128 v[0:3], v192 offset:32768
	ds_read_b128 v[4:7], v192 offset:40960
	s_waitcnt vmcnt(5) lgkmcnt(1)
	v_mfma_f32_32x32x16_bf16 v[16:31], v[0:3], v[120:123], v[16:31]
	v_add_u32_e32 v0, 0x60, v180
	v_xad_u32 v0, v0, v66, v65
	v_add_u32_e32 v191, 0x8000, v0
	s_waitcnt lgkmcnt(0)
	v_mfma_f32_32x32x16_bf16 v[32:47], v[4:7], v[120:123], v[32:47]
	ds_read_b128 v[0:3], v191 offset:32768
	ds_read_b128 v[4:7], v191 offset:40960
	s_waitcnt vmcnt(4) lgkmcnt(1)
	v_mfma_f32_32x32x16_bf16 v[16:31], v[0:3], v[124:127], v[16:31]
	v_add_u32_e32 v0, 0x80, v180
	v_xad_u32 v0, v0, v66, v65
	v_add_u32_e32 v190, 0x8000, v0
	ds_read_b128 v[0:3], v189 offset:32896
	s_waitcnt lgkmcnt(1)
	v_mfma_f32_32x32x16_bf16 v[32:47], v[4:7], v[124:127], v[32:47]
	ds_read_b128 v[4:7], v189 offset:41088
	s_waitcnt vmcnt(3) lgkmcnt(1)
	v_mfma_f32_32x32x16_bf16 v[16:31], v[0:3], v[116:119], v[16:31]
	v_and_b32_e32 v0, 0xc0, v48
	v_and_or_b32 v11, v64, 24, v0
	v_add_u32_e32 v0, 0xa0, v180
	v_xad_u32 v0, v0, v66, v65
	v_add_u32_e32 v198, 0x8000, v0
	ds_read_b128 v[0:3], v199 offset:32896
	s_waitcnt lgkmcnt(1)
; #define SLOAD(i, k0) do { sr_[i].vs0 = St::ld8(&Vh[(long)((k0) + sr) * LDK + sc]); sr_[i].vs1 = St::ld8(&Vh[(long)((k0) + 32 + sr) * LDK + sc]); \
;     sr_[i].ks0 = St::ld8(&Kh[(long)((k0) + sr) * LDK + sc]); sr_[i].ks1 = St::ld8(&Kh[(long)((k0) + 32 + sr) * LDK + sc]); } while (0)
; #define SWAIT() do { if constexpr (SDEPTH == 2) asm volatile("s_waitcnt vmcnt(4)" ::: "memory"); else asm volatile("s_waitcnt vmcnt(0)" ::: "memory"); } while (0)
; __device__ __forceinline__ void partialSM(f32x16& p0, f32x16& p1, float& m_reg, float& mn, float& alpha) {
;   constexpr float C = SCALE * 1.4426950408889634f;
;   float pmax = p0[0]; for (int r = 1; r < 16; ++r) pmax = fmaxf(pmax, p0[r]); for (int r = 0; r < 16; ++r) pmax = fmaxf(pmax, p1[r]);
;   { auto rr = __builtin_amdgcn_permlane32_swap(__float_as_uint(pmax), __float_as_uint(pmax), false, false);
;     pmax = fmaxf(__uint_as_float(rr[0]), __uint_as_float(rr[1])); }
;   if (__builtin_expect(__all(pmax - m_reg <= THR / SCALE), 1)) { mn = m_reg; alpha = 1.f; }
;   else { mn = fmaxf(m_reg, pmax); alpha = __builtin_amdgcn_exp2f((m_reg - mn) * C); m_reg = mn; }
;   float mnC = -mn * C;
;   for (int r = 0; r < 16; ++r) p0[r] = fmaf(p0[r], C, mnC); for (int r = 0; r < 16; ++r) p1[r] = fmaf(p1[r], C, mnC);
;   for (int r = 0; r < 16; ++r) p0[r] = __builtin_amdgcn_exp2f(p0[r]);
; template <typename TQ>
; __device__ __forceinline__ void attn_dense_body(const TQ* __restrict__ Qb, const bf16* __restrict__ Kh, const bf16* __restrict__ Vh,
;                                                 unsigned short* __restrict__ Ob, int seq, char* lds, const int wave_s) {
;     ...
;   qkt(pA0, pA1, K_lds, qr, r32, hi); partialSM(pA0, pA1, m_reg, mnA, alA);
;   SLOAD(SO, KVBLK); if constexpr (SDEPTH == 2) { if (2 < NT) SLOAD(SE, 2 * KVBLK); }
;   SWAIT(); SWRITE(1, SO); __syncthreads();
	v_mfma_f32_32x32x16_bf16 v[32:47], v[4:7], v[116:119], v[32:47]
	v_add_u32_e32 v4, 64, v69
	v_mad_i64_i32 v[4:5], s[46:47], v4, s97, 0
	v_or_b32_e32 v4, v4, v70
	v_lshl_add_u64 v[8:9], v[4:5], 1, s[38:39]
	ds_read_b128 v[4:7], v199 offset:41088
	global_load_dwordx4 v[48:51], v[8:9], off offset:2560
	s_waitcnt vmcnt(3) lgkmcnt(1)
	v_mfma_f32_32x32x16_bf16 v[16:31], v[0:3], v[104:107], v[16:31]
	v_add_u32_e32 v0, 0x60, v69
	v_mad_i64_i32 v[0:1], s[46:47], v0, s97, 0
	v_or_b32_e32 v0, v0, v70
	v_lshl_add_u64 v[0:1], v[0:1], 1, s[38:39]
	global_load_dwordx4 v[52:55], v[0:1], off offset:2560
	global_load_dwordx4 v[56:59], v[8:9], off offset:2048
	global_load_dwordx4 v[60:63], v[0:1], off offset:2048
	ds_read_b128 v[0:3], v192 offset:32896
	s_waitcnt lgkmcnt(1)
	v_mfma_f32_32x32x16_bf16 v[32:47], v[4:7], v[104:107], v[32:47]
	v_and_b32_e32 v4, 32, v10
	v_and_b32_e32 v5, 0x100, v64
	v_or3_b32 v71, v11, v4, v5
	ds_read_b128 v[4:7], v192 offset:41088
	v_add_u32_e32 v184, s51, v71
	s_waitcnt vmcnt(5) lgkmcnt(1)
	v_mfma_f32_32x32x16_bf16 v[16:31], v[0:3], v[100:103], v[16:31]
	v_add_u32_e32 v0, 0xe0, v180
	v_xad_u32 v0, v0, v66, v65
	v_add_u32_e32 v200, 0x8000, v0
	ds_read_b128 v[0:3], v191 offset:32896
	ds_read_b128 v[64:67], v191 offset:41088
	s_waitcnt lgkmcnt(2)
	v_mfma_f32_32x32x16_bf16 v[32:47], v[4:7], v[100:103], v[32:47]
	s_waitcnt vmcnt(4) lgkmcnt(1)
	v_mfma_f32_32x32x16_bf16 v[16:31], v[0:3], v[96:99], v[16:31]
	v_mov_b64_e32 v[0:1], s[80:81]
	v_mov_b64_e32 v[14:15], s[94:95]
	v_mov_b64_e32 v[2:3], s[82:83]
	v_mov_b64_e32 v[4:5], s[84:85]
	v_mov_b64_e32 v[6:7], s[86:87]
	v_mov_b64_e32 v[8:9], s[88:89]
	v_mov_b64_e32 v[10:11], s[90:91]
	s_waitcnt lgkmcnt(0)
	v_mfma_f32_32x32x16_bf16 v[32:47], v[64:67], v[96:99], v[32:47]
	s_nop 2
	v_max_f32_e32 v64, v17, v17
	v_max_f32_e32 v65, v16, v16
	v_max_f32_e32 v64, v65, v64
	v_max3_f32 v64, v64, v18, v19
	v_max3_f32 v64, v64, v20, v21
	v_max3_f32 v64, v64, v22, v23
	v_max3_f32 v64, v64, v24, v25
	v_max3_f32 v64, v64, v26, v27
	v_max3_f32 v64, v64, v28, v29
	v_max3_f32 v64, v64, v30, v31
	v_max3_f32 v64, v64, v32, v33
	v_max3_f32 v64, v64, v34, v35
	v_max3_f32 v64, v64, v36, v37
	v_max3_f32 v64, v64, v38, v39
	v_max3_f32 v64, v64, v40, v41
	v_max3_f32 v64, v64, v42, v43
	v_max3_f32 v64, v64, v44, v45
	v_max3_f32 v64, v64, v46, v47
	v_mov_b32_e32 v65, v64
	s_nop 1
	v_permlane32_swap_b32_e32 v64, v65
	v_max_f32_e32 v73, v64, v64
	v_add_u32_e32 v64, 0x80, v69
	v_max_f32_e32 v72, v65, v65
	v_mad_i64_i32 v[64:65], s[46:47], v64, s97, 0
	v_add_u32_e32 v66, 0xa0, v69
	v_or_b32_e32 v64, v64, v70
	v_mad_i64_i32 v[66:67], s[46:47], v66, s97, 0
	v_lshl_add_u64 v[64:65], v[64:65], 1, s[38:39]
	v_or_b32_e32 v66, v66, v70
	v_lshl_add_u64 v[66:67], v[66:67], 1, s[38:39]
	global_load_dwordx4 v[128:131], v[64:65], off offset:2560
	global_load_dwordx4 v[132:135], v[64:65], off offset:2048
	global_load_dwordx4 v[136:139], v[66:67], off offset:2560
	global_load_dwordx4 v[140:143], v[66:67], off offset:2048
	v_max_f32_e32 v64, v73, v72
	s_waitcnt vmcnt(4)
	s_waitcnt vmcnt(7)
	ds_write_b128 v187, v[48:51] offset:16384
	s_waitcnt vmcnt(6)
	ds_write_b128 v187, v[52:55] offset:24576
	s_waitcnt vmcnt(5)
	ds_write_b128 v185, v[56:59] offset:49152
	s_waitcnt vmcnt(4)
	ds_write_b128 v185, v[60:63] offset:57344
	v_xor_b32_e32 v185, 0x18000, v185
	v_xor_b32_e32 v187, 0x8000, v187
	v_max_f32_e32 v48, 0xf149f2ca, v64
	v_sub_f32_e32 v49, 0xf149f2ca, v48
	v_mul_f32_e32 v49, 0x3e0293ee, v49
	v_add_f32_e32 v65, 0x7149f2ca, v64
	v_exp_f32_e32 v49, v49
	v_cmp_ge_f32_e32 vcc, s9, v65
	s_cmp_eq_u64 vcc, exec
	s_cselect_b64 vcc, -1, 0
	v_cndmask_b32_e64 v202, v49, 1.0, vcc
	v_mov_b32_e32 v49, 0xf149f2ca
	v_cndmask_b32_e32 v164, v48, v49, vcc
	v_mul_f32_e32 v48, 0xbe0293ee, v164
	v_fmamk_f32 v16, v16, 0x3e0293ee, v48
	v_exp_f32_e32 v161, v16
	v_fmamk_f32 v16, v17, 0x3e0293ee, v48
	v_exp_f32_e32 v175, v16
	v_fmamk_f32 v16, v18, 0x3e0293ee, v48
	v_exp_f32_e32 v162, v16
	v_fmamk_f32 v16, v19, 0x3e0293ee, v48
	v_exp_f32_e32 v206, v16
	v_fmamk_f32 v16, v20, 0x3e0293ee, v48
	v_exp_f32_e32 v174, v16
	v_fmamk_f32 v16, v21, 0x3e0293ee, v48
	v_exp_f32_e32 v209, v16
	v_fmamk_f32 v16, v22, 0x3e0293ee, v48
	v_exp_f32_e32 v163, v16
	v_fmamk_f32 v16, v23, 0x3e0293ee, v48
	v_exp_f32_e32 v173, v16
	v_fmamk_f32 v16, v24, 0x3e0293ee, v48
	v_exp_f32_e32 v169, v16
	v_fmamk_f32 v16, v25, 0x3e0293ee, v48
	v_exp_f32_e32 v171, v16
	v_fmamk_f32 v16, v26, 0x3e0293ee, v48
	v_exp_f32_e32 v170, v16
	v_fmamk_f32 v16, v27, 0x3e0293ee, v48
	s_addk_i32 s51, 0x4000
	v_exp_f32_e32 v172, v16
	v_fmamk_f32 v16, v28, 0x3e0293ee, v48
	s_add_u32 s40, s40, s44
	v_exp_f32_e32 v165, v16
	v_fmamk_f32 v16, v29, 0x3e0293ee, v48
	s_addc_u32 s41, s41, s45
	v_pk_fma_f32 v[144:145], v[46:47], s[30:31], v[48:49] op_sel_hi:[1,0,0]
	v_pk_fma_f32 v[150:151], v[44:45], s[30:31], v[48:49] op_sel_hi:[1,0,0]
	v_pk_fma_f32 v[154:155], v[42:43], s[30:31], v[48:49] op_sel_hi:[1,0,0]
	v_pk_fma_f32 v[146:147], v[40:41], s[30:31], v[48:49] op_sel_hi:[1,0,0]
	v_pk_fma_f32 v[148:149], v[38:39], s[30:31], v[48:49] op_sel_hi:[1,0,0]
	v_pk_fma_f32 v[152:153], v[36:37], s[30:31], v[48:49] op_sel_hi:[1,0,0]
	v_pk_fma_f32 v[156:157], v[34:35], s[30:31], v[48:49] op_sel_hi:[1,0,0]
	v_pk_fma_f32 v[158:159], v[32:33], s[30:31], v[48:49] op_sel_hi:[1,0,0]
	v_exp_f32_e32 v167, v16
	v_fmamk_f32 v16, v30, 0x3e0293ee, v48
	v_fmac_f32_e32 v48, 0x3e0293ee, v31
	s_lshl_b64 s[40:41], s[40:41], 1
	v_readlane_b32 s44, v255, 53
	v_exp_f32_e32 v166, v16
	v_exp_f32_e32 v168, v48
	v_mad_i64_i32 v[16:17], s[46:47], v69, s33, 0
	v_and_b32_e32 v18, 15, v68
	s_add_u32 s40, s44, s40
	v_readlane_b32 s44, v255, 54
	v_lshl_or_b32 v16, v18, 4, v16
	s_addc_u32 s41, s44, s41
	v_mov_b64_e32 v[12:13], s[92:93]
	v_mov_b32_e32 v176, v16
	v_add_u32_e32 v177, 0x18000, v16
	v_add_u32_e32 v183, 0x30000, v16
	v_add_u32_e32 v186, 0x48000, v16
	s_add_u32 s52, s40, 0xfffb8000
	s_addc_u32 s53, s41, -1
	v_mov_b64_e32 v[62:63], v[14:15]
	v_mov_b64_e32 v[46:47], v[14:15]
	v_mov_b64_e32 v[30:31], v[14:15]
	v_cmp_gt_u32_e64 s[38:39], 32, v68
	v_mov_b64_e32 v[60:61], v[12:13]
	v_mov_b64_e32 v[58:59], v[10:11]
	v_mov_b64_e32 v[56:57], v[8:9]
	v_mov_b64_e32 v[54:55], v[6:7]
	v_mov_b64_e32 v[52:53], v[4:5]
	v_mov_b64_e32 v[50:51], v[2:3]
	v_mov_b64_e32 v[48:49], v[0:1]
	v_mov_b64_e32 v[44:45], v[12:13]
	v_mov_b64_e32 v[42:43], v[10:11]
	v_mov_b64_e32 v[40:41], v[8:9]
	v_mov_b64_e32 v[38:39], v[6:7]
	v_mov_b64_e32 v[36:37], v[4:5]
	v_mov_b64_e32 v[34:35], v[2:3]
	v_mov_b64_e32 v[32:33], v[0:1]
	v_mov_b64_e32 v[28:29], v[12:13]
	v_mov_b64_e32 v[26:27], v[10:11]
	v_mov_b64_e32 v[24:25], v[8:9]
	v_mov_b64_e32 v[22:23], v[6:7]
	v_mov_b64_e32 v[20:21], v[4:5]
	v_mov_b64_e32 v[18:19], v[2:3]
	v_mov_b64_e32 v[16:17], v[0:1]
	s_mov_b64 s[94:95], s[16:17]
	s_mov_b64 s[84:85], s[12:13]
	s_waitcnt lgkmcnt(0)
	s_barrier
; #define SBAR() __builtin_amdgcn_sched_barrier(0)
; #define SLOAD(i, k0) do { sr_[i].vs0 = St::ld8(&Vh[(long)((k0) + sr) * LDK + sc]); sr_[i].vs1 = St::ld8(&Vh[(long)((k0) + 32 + sr) * LDK + sc]); \
;     sr_[i].ks0 = St::ld8(&Kh[(long)((k0) + sr) * LDK + sc]); sr_[i].ks1 = St::ld8(&Kh[(long)((k0) + 32 + sr) * LDK + sc]); } while (0)
; __device__ __forceinline__ void finishSM(f32x16& p0, f32x16& p1, float alpha, float& l_reg, bf16x8& pa0, bf16x8& pa1, bf16x8& pa2, bf16x8& pa3) {
;   for (int r = 0; r < 16; ++r) p1[r] = __builtin_amdgcn_exp2f(p1[r]);
;   float ps = 0; for (int r = 0; r < 16; ++r) ps += p0[r]; for (int r = 0; r < 16; ++r) ps += p1[r];
;   { auto rr = __builtin_amdgcn_permlane32_swap(__float_as_uint(ps), __float_as_uint(ps), false, false);
;     ps = __uint_as_float(rr[0]) + __uint_as_float(rr[1]); }
;   l_reg = l_reg * alpha + ps;
;     ...
;   PK4(p0, 0, pa0); PK4(p0, 8, pa1); PK4(p1, 0, pa2); PK4(p1, 8, pa3);
; template <typename TQ>
; __device__ __forceinline__ void attn_dense_body(const TQ* __restrict__ Qb, const bf16* __restrict__ Kh, const bf16* __restrict__ Vh,
;                                                 unsigned short* __restrict__ Ob, int seq, char* lds, const int wave_s) {
;     ...
;     SBAR(); qkt(pB0, pB1, (bf16*)((char*)K_lds + SHM_K), qr, r32, hi);
;     finishSM(pA0, pA1, alA, l_reg, pa0, pa1, pa2, pa3); SBAR();
;     SLOAD(SO, (j + SDEPTH) * KVBLK); SBAR();
;     pv_d0(o, vb0, pa0, pa1, pa2, pa3); partialSM(pB0, pB1, m_reg, mnB, alB);
.LBB0_575:
	ds_read_b128 v[64:67], v189 offset:49152
	ds_read_b128 v[68:71], v189 offset:57344
	ds_read_b128 v[210:213], v199 offset:49152
	ds_read_b128 v[214:217], v199 offset:57344
	ds_read_b128 v[240:243], v192 offset:49152
	ds_read_b128 v[244:247], v192 offset:57344
	v_add_f32_e32 v160, v175, v161
	s_waitcnt lgkmcnt(4)
	v_mfma_f32_32x32x16_bf16 v[80:95], v[64:67], v[112:115], 0
	v_add_f32_e32 v160, v162, v160
	v_add_f32_e32 v160, v206, v160
	v_add_f32_e32 v160, v174, v160
	v_add_f32_e32 v160, v209, v160
	v_add_f32_e32 v160, v163, v160
	v_add_f32_e32 v160, v173, v160
	v_add_f32_e32 v160, v169, v160
	v_mfma_f32_32x32x16_bf16 v[64:79], v[68:71], v[112:115], 0
	v_add_f32_e32 v160, v171, v160
	v_add_f32_e32 v160, v170, v160
	v_add_f32_e32 v160, v172, v160
	v_exp_f32_e32 v158, v158
	v_add_f32_e32 v160, v165, v160
	v_exp_f32_e32 v159, v159
	v_add_f32_e32 v160, v167, v160
	s_waitcnt lgkmcnt(2)
	v_mfma_f32_32x32x16_bf16 v[80:95], v[210:213], v[108:111], v[80:95]
	v_exp_f32_e32 v156, v156
	v_add_f32_e32 v160, v166, v160
	v_exp_f32_e32 v157, v157
	v_add_f32_e32 v160, v168, v160
	v_exp_f32_e32 v152, v152
	v_add_f32_e32 v160, v158, v160
	v_exp_f32_e32 v153, v153
	v_mfma_f32_32x32x16_bf16 v[64:79], v[214:217], v[108:111], v[64:79]
	ds_read_b128 v[210:213], v191 offset:49152
	ds_read_b128 v[214:217], v191 offset:57344
	v_add_f32_e32 v160, v159, v160
	v_exp_f32_e32 v148, v148
	v_add_f32_e32 v160, v156, v160
	v_exp_f32_e32 v149, v149
	v_add_f32_e32 v160, v157, v160
	v_exp_f32_e32 v146, v146
	s_waitcnt lgkmcnt(2)
	v_mfma_f32_32x32x16_bf16 v[80:95], v[240:243], v[120:123], v[80:95]
	v_add_f32_e32 v160, v152, v160
	v_exp_f32_e32 v147, v147
	v_add_f32_e32 v160, v153, v160
	v_exp_f32_e32 v154, v154
	v_add_f32_e32 v160, v148, v160
	v_exp_f32_e32 v155, v155
	v_add_f32_e32 v160, v149, v160
	v_mfma_f32_32x32x16_bf16 v[64:79], v[244:247], v[120:123], v[64:79]
	ds_read_b128 v[240:243], v189 offset:49280
	ds_read_b128 v[244:247], v189 offset:57472
	v_exp_f32_e32 v150, v150
	v_add_f32_e32 v160, v146, v160
	v_exp_f32_e32 v151, v151
	v_add_f32_e32 v160, v147, v160
	v_exp_f32_e32 v144, v144
	v_add_f32_e32 v160, v154, v160
	s_waitcnt lgkmcnt(2)
	v_mfma_f32_32x32x16_bf16 v[80:95], v[210:213], v[124:127], v[80:95]
	v_exp_f32_e32 v145, v145
	v_add_f32_e32 v160, v155, v160
	v_add_f32_e32 v160, v150, v160
	v_add_f32_e32 v160, v151, v160
	v_add_f32_e32 v160, v144, v160
	v_add_f32_e32 v203, v145, v160
	v_mfma_f32_32x32x16_bf16 v[64:79], v[214:217], v[124:127], v[64:79]
	ds_read_b128 v[210:213], v199 offset:49280
	ds_read_b128 v[214:217], v199 offset:57472
	s_waitcnt lgkmcnt(2)
	v_mfma_f32_32x32x16_bf16 v[80:95], v[240:243], v[116:119], v[80:95]
	v_mfma_f32_32x32x16_bf16 v[64:79], v[244:247], v[116:119], v[64:79]
	ds_read_b128 v[240:243], v192 offset:49280
	ds_read_b128 v[244:247], v192 offset:57472
	s_waitcnt lgkmcnt(2)
	v_mfma_f32_32x32x16_bf16 v[80:95], v[210:213], v[104:107], v[80:95]
	v_mfma_f32_32x32x16_bf16 v[64:79], v[214:217], v[104:107], v[64:79]
	ds_read_b128 v[210:213], v191 offset:49280
	ds_read_b128 v[214:217], v191 offset:57472
	s_waitcnt lgkmcnt(2)
	v_mfma_f32_32x32x16_bf16 v[80:95], v[240:243], v[100:103], v[80:95]
	v_mfma_f32_32x32x16_bf16 v[64:79], v[244:247], v[100:103], v[64:79]
	v_cvt_pk_bf16_f32 v160, v161, v175
	v_cvt_pk_bf16_f32 v161, v162, v206
	v_cvt_pk_bf16_f32 v162, v174, v209
	v_cvt_pk_bf16_f32 v163, v163, v173
	v_cvt_pk_bf16_f32 v206, v169, v171
	v_cvt_pk_bf16_f32 v207, v170, v172
	s_waitcnt lgkmcnt(0)
	v_mfma_f32_32x32x16_bf16 v[80:95], v[210:213], v[96:99], v[80:95]
	v_cvt_pk_bf16_f32 v208, v165, v167
	v_cvt_pk_bf16_f32 v209, v166, v168
	v_cvt_pk_bf16_f32 v166, v158, v159
	v_cvt_pk_bf16_f32 v167, v156, v157
	v_cvt_pk_bf16_f32 v168, v152, v153
	v_mfma_f32_32x32x16_bf16 v[64:79], v[214:217], v[96:99], v[64:79]
	v_cvt_pk_bf16_f32 v169, v148, v149
	v_cvt_pk_bf16_f32 v170, v146, v147
	v_cvt_pk_bf16_f32 v171, v154, v155
	v_cvt_pk_bf16_f32 v172, v150, v151
	v_cvt_pk_bf16_f32 v173, v144, v145
	global_load_dwordx4 v[144:147], v176, s[52:53]
	global_load_dwordx4 v[148:151], v176, s[52:53] offset:-512
	global_load_dwordx4 v[156:159], v177, s[52:53]
	global_load_dwordx4 v[152:155], v177, s[52:53] offset:-512
	ds_read_b64_tr_b16 v[210:211], v184 offset:0
	ds_read_b64_tr_b16 v[212:213], v184 offset:0x800
	ds_read_b64_tr_b16 v[214:215], v184 offset:0x1000
	ds_read_b64_tr_b16 v[216:217], v184 offset:0x1800
	ds_read_b64_tr_b16 v[224:225], v184 offset:0x2000
	ds_read_b64_tr_b16 v[226:227], v184 offset:0x2800
	ds_read_b64_tr_b16 v[228:229], v184 offset:0x3000
	ds_read_b64_tr_b16 v[230:231], v184 offset:0x3800
	s_waitcnt lgkmcnt(0)
	v_mfma_f32_32x32x16_bf16 v[0:15], v[160:163], v[210:213], v[0:15]
	ds_read_b64_tr_b16 v[210:211], v184 offset:0x200
	ds_read_b64_tr_b16 v[212:213], v184 offset:0xa00
	v_mfma_f32_32x32x16_bf16 v[0:15], v[206:209], v[214:217], v[0:15]
	ds_read_b64_tr_b16 v[214:215], v184 offset:0x1200
	ds_read_b64_tr_b16 v[216:217], v184 offset:0x1a00
	v_mfma_f32_32x32x16_bf16 v[0:15], v[166:169], v[224:227], v[0:15]
	ds_read_b64_tr_b16 v[224:225], v184 offset:0x2200
	ds_read_b64_tr_b16 v[226:227], v184 offset:0x2a00
	v_mfma_f32_32x32x16_bf16 v[0:15], v[170:173], v[228:231], v[0:15]
	ds_read_b64_tr_b16 v[228:229], v184 offset:0x3200
	ds_read_b64_tr_b16 v[230:231], v184 offset:0x3a00
	s_waitcnt lgkmcnt(0)
; #define SBAR() __builtin_amdgcn_sched_barrier(0)
; __device__ __forceinline__ void partialSM(f32x16& p0, f32x16& p1, float& m_reg, float& mn, float& alpha) {
;   constexpr float C = SCALE * 1.4426950408889634f;
;   float pmax = p0[0]; for (int r = 1; r < 16; ++r) pmax = fmaxf(pmax, p0[r]); for (int r = 0; r < 16; ++r) pmax = fmaxf(pmax, p1[r]);
;   { auto rr = __builtin_amdgcn_permlane32_swap(__float_as_uint(pmax), __float_as_uint(pmax), false, false);
;     pmax = fmaxf(__uint_as_float(rr[0]), __uint_as_float(rr[1])); }
;   if (__builtin_expect(__all(pmax - m_reg <= THR / SCALE), 1)) { mn = m_reg; alpha = 1.f; }
; template <int D0> __device__ __forceinline__ void pv_one(f32x16& od, int vb, bf16x8 pa0, bf16x8 pa1, bf16x8 pa2, bf16x8 pa3) {
;   const s16x4 l0 = tr_read<v_rd_off(D0, 0, 0)>(vb), h0 = tr_read<v_rd_off(D0, 0, 1)>(vb), l1 = tr_read<v_rd_off(D0, 1, 0)>(vb), h1 = tr_read<v_rd_off(D0, 1, 1)>(vb);
;   const s16x4 l2 = tr_read<v_rd_off(D0, 2, 0)>(vb), h2 = tr_read<v_rd_off(D0, 2, 1)>(vb), l3 = tr_read<v_rd_off(D0, 3, 0)>(vb), h3 = tr_read<v_rd_off(D0, 3, 1)>(vb);
;   asm volatile("s_waitcnt lgkmcnt(0)" ::: "memory"); SBAR();
;     ...
;   od = __builtin_amdgcn_mfma_f32_32x32x16_bf16(pa0, PK(l0, h0), od, 0, 0, 0);
;   od = __builtin_amdgcn_mfma_f32_32x32x16_bf16(pa1, PK(l1, h1), od, 0, 0, 0);
;   od = __builtin_amdgcn_mfma_f32_32x32x16_bf16(pa2, PK(l2, h2), od, 0, 0, 0);
;   od = __builtin_amdgcn_mfma_f32_32x32x16_bf16(pa3, PK(l3, h3), od, 0, 0, 0);
;     ...
; }
; __device__ __forceinline__ void pv_d0(f32x16* o, int vb, bf16x8 pa0, bf16x8 pa1, bf16x8 pa2, bf16x8 pa3) {
;   pv_one<0>(o[0], vb, pa0, pa1, pa2, pa3); pv_one<1>(o[1], vb, pa0, pa1, pa2, pa3); pv_one<2>(o[2], vb, pa0, pa1, pa2, pa3); pv_one<3>(o[3], vb, pa0, pa1, pa2, pa3);
	v_mfma_f32_32x32x16_bf16 v[48:63], v[160:163], v[210:213], v[48:63]
	ds_read_b64_tr_b16 v[210:211], v184 offset:0x400
	ds_read_b64_tr_b16 v[212:213], v184 offset:0xc00
	v_mfma_f32_32x32x16_bf16 v[48:63], v[206:209], v[214:217], v[48:63]
	ds_read_b64_tr_b16 v[214:215], v184 offset:0x1400
	ds_read_b64_tr_b16 v[216:217], v184 offset:0x1c00
	v_mfma_f32_32x32x16_bf16 v[48:63], v[166:169], v[224:227], v[48:63]
	ds_read_b64_tr_b16 v[224:225], v184 offset:0x2400
	ds_read_b64_tr_b16 v[226:227], v184 offset:0x2c00
	v_mfma_f32_32x32x16_bf16 v[48:63], v[170:173], v[228:231], v[48:63]
	ds_read_b64_tr_b16 v[228:229], v184 offset:0x3400
	ds_read_b64_tr_b16 v[230:231], v184 offset:0x3c00
	s_waitcnt lgkmcnt(0)
	v_mfma_f32_32x32x16_bf16 v[32:47], v[160:163], v[210:213], v[32:47]
	ds_read_b64_tr_b16 v[210:211], v184 offset:0x600
	ds_read_b64_tr_b16 v[212:213], v184 offset:0xe00
	v_mfma_f32_32x32x16_bf16 v[32:47], v[206:209], v[214:217], v[32:47]
	ds_read_b64_tr_b16 v[214:215], v184 offset:0x1600
	ds_read_b64_tr_b16 v[216:217], v184 offset:0x1e00
	v_mfma_f32_32x32x16_bf16 v[32:47], v[166:169], v[224:227], v[32:47]
	ds_read_b64_tr_b16 v[224:225], v184 offset:0x2600
	ds_read_b64_tr_b16 v[226:227], v184 offset:0x2e00
	v_mfma_f32_32x32x16_bf16 v[32:47], v[170:173], v[228:231], v[32:47]
	ds_read_b64_tr_b16 v[228:229], v184 offset:0x3600
	ds_read_b64_tr_b16 v[230:231], v184 offset:0x3e00
	s_waitcnt lgkmcnt(0)
	v_mfma_f32_32x32x16_bf16 v[16:31], v[160:163], v[210:213], v[16:31]
	v_max_f32_e32 v160, v80, v81
	v_max3_f32 v160, v160, v82, v83
	v_max3_f32 v160, v160, v84, v85
	v_max3_f32 v160, v160, v86, v87
	v_max3_f32 v160, v160, v88, v89
	v_max3_f32 v160, v160, v90, v91
	v_max3_f32 v160, v160, v92, v93
	v_mfma_f32_32x32x16_bf16 v[16:31], v[206:209], v[214:217], v[16:31]
	v_max3_f32 v160, v160, v94, v95
	v_max3_f32 v160, v160, v64, v65
	v_max3_f32 v160, v160, v66, v67
	v_max3_f32 v160, v160, v68, v69
	v_max3_f32 v160, v160, v70, v71
	v_max3_f32 v160, v160, v72, v73
	v_max3_f32 v160, v160, v74, v75
	v_max3_f32 v160, v160, v76, v77
	v_mfma_f32_32x32x16_bf16 v[16:31], v[166:169], v[224:227], v[16:31]
	v_max3_f32 v160, v160, v78, v79
	v_mov_b32_e32 v161, v160
	s_nop 1
	v_permlane32_swap_b32_e32 v160, v161
	v_max_f32_e32 v160, v160, v161
	v_sub_f32_e32 v161, v160, v164
	v_cmp_ge_f32_e32 vcc, s9, v161
	v_mfma_f32_32x32x16_bf16 v[16:31], v[170:173], v[228:231], v[16:31]
	s_cmp_eq_u64 vcc, exec
	s_cbranch_scc0 .Lattn_slow_a
	v_mov_b32_e32 v205, 1.0
	v_mov_b32_e32 v206, v164
	s_waitcnt vmcnt(4)
	ds_write_b128 v187, v[128:131]
	ds_write_b128 v187, v[136:139] offset:8192
	ds_write_b128 v185, v[132:135] offset:32768
	ds_write_b128 v185, v[140:143] offset:40960
; #define SBAR() __builtin_amdgcn_sched_barrier(0)
; #define SLOAD(i, k0) do { sr_[i].vs0 = St::ld8(&Vh[(long)((k0) + sr) * LDK + sc]); sr_[i].vs1 = St::ld8(&Vh[(long)((k0) + 32 + sr) * LDK + sc]); \
;     sr_[i].ks0 = St::ld8(&Kh[(long)((k0) + sr) * LDK + sc]); sr_[i].ks1 = St::ld8(&Kh[(long)((k0) + 32 + sr) * LDK + sc]); } while (0)
; #define RESC(a) do { if (__any((a) < 1.f)) { if (hi == 0) al_l[r32] = (a); asm volatile("s_waitcnt lgkmcnt(0)" ::: "memory"); \
;     for (int d = 0; d < 4; ++d) for (int r = 0; r < 16; ++r) o[d][r] *= al_l[crow(r, hi)]; } } while (0)
; __device__ __forceinline__ void partialSM(f32x16& p0, f32x16& p1, float& m_reg, float& mn, float& alpha) {
;     ...
;   float mnC = -mn * C;
;   for (int r = 0; r < 16; ++r) p0[r] = fmaf(p0[r], C, mnC); for (int r = 0; r < 16; ++r) p1[r] = fmaf(p1[r], C, mnC);
;   for (int r = 0; r < 16; ++r) p0[r] = __builtin_amdgcn_exp2f(p0[r]);
; }
; __device__ __forceinline__ void finishSM(f32x16& p0, f32x16& p1, float alpha, float& l_reg, bf16x8& pa0, bf16x8& pa1, bf16x8& pa2, bf16x8& pa3) {
;   for (int r = 0; r < 16; ++r) p1[r] = __builtin_amdgcn_exp2f(p1[r]);
;   float ps = 0; for (int r = 0; r < 16; ++r) ps += p0[r]; for (int r = 0; r < 16; ++r) ps += p1[r];
;   { auto rr = __builtin_amdgcn_permlane32_swap(__float_as_uint(ps), __float_as_uint(ps), false, false);
;     ps = __uint_as_float(rr[0]) + __uint_as_float(rr[1]); }
;   l_reg = l_reg * alpha + ps;
;     ...
;   PK4(p0, 0, pa0); PK4(p0, 8, pa1); PK4(p1, 0, pa2); PK4(p1, 8, pa3);
; template <typename TQ>
; __device__ __forceinline__ void attn_dense_body(const TQ* __restrict__ Qb, const bf16* __restrict__ Kh, const bf16* __restrict__ Vh,
;                                                 unsigned short* __restrict__ Ob, int seq, char* lds, const int wave_s) {
;     ...
;     RESC(alB); __syncthreads();
;     SBAR(); qkt(pA0, pA1, K_lds, qr, r32, hi);
;     finishSM(pB0, pB1, alB, l_reg, pa0, pa1, pa2, pa3); SBAR();
;     if (SDEPTH == 1 || j + 3 < NT) SLOAD(SE, (j + 1 + SDEPTH) * KVBLK); SBAR();
.LBB0_579:
	v_xor_b32_e32 v189, 0x18000, v189
	v_xor_b32_e32 v199, 0x18000, v199
	v_xor_b32_e32 v192, 0x18000, v192
	v_xor_b32_e32 v191, 0x18000, v191
	v_mul_f32_e32 v207, 0xbe0293ee, v206
	v_fmamk_f32 v80, v80, 0x3e0293ee, v207
	v_fmamk_f32 v81, v81, 0x3e0293ee, v207
	v_fmamk_f32 v82, v82, 0x3e0293ee, v207
	v_fmamk_f32 v83, v83, 0x3e0293ee, v207
	v_fmamk_f32 v84, v84, 0x3e0293ee, v207
	v_fmamk_f32 v85, v85, 0x3e0293ee, v207
	v_fmamk_f32 v86, v86, 0x3e0293ee, v207
	v_fmamk_f32 v87, v87, 0x3e0293ee, v207
	v_fmamk_f32 v88, v88, 0x3e0293ee, v207
	v_fmamk_f32 v89, v89, 0x3e0293ee, v207
	v_fmamk_f32 v90, v90, 0x3e0293ee, v207
	v_fmamk_f32 v91, v91, 0x3e0293ee, v207
	v_fmamk_f32 v92, v92, 0x3e0293ee, v207
	v_fmamk_f32 v93, v93, 0x3e0293ee, v207
	v_fmamk_f32 v94, v94, 0x3e0293ee, v207
	v_fmamk_f32 v95, v95, 0x3e0293ee, v207
	v_exp_f32_e32 v160, v80
	v_exp_f32_e32 v175, v81
	v_exp_f32_e32 v161, v82
	v_exp_f32_e32 v174, v83
	v_exp_f32_e32 v162, v84
	v_exp_f32_e32 v173, v85
	v_exp_f32_e32 v163, v86
	v_exp_f32_e32 v172, v87
	v_exp_f32_e32 v164, v88
	v_exp_f32_e32 v171, v89
	v_exp_f32_e32 v165, v90
	v_exp_f32_e32 v170, v91
	v_exp_f32_e32 v166, v92
	v_exp_f32_e32 v169, v93
	v_exp_f32_e32 v167, v94
	v_exp_f32_e32 v168, v95
	v_fmamk_f32 v216, v64, 0x3e0293ee, v207
	v_fmamk_f32 v217, v65, 0x3e0293ee, v207
	v_fmamk_f32 v218, v66, 0x3e0293ee, v207
	v_fmamk_f32 v219, v67, 0x3e0293ee, v207
	v_fmamk_f32 v224, v68, 0x3e0293ee, v207
	v_fmamk_f32 v209, v69, 0x3e0293ee, v207
	v_fmamk_f32 v210, v70, 0x3e0293ee, v207
	v_fmamk_f32 v211, v71, 0x3e0293ee, v207
	v_fmamk_f32 v212, v72, 0x3e0293ee, v207
	v_fmamk_f32 v213, v73, 0x3e0293ee, v207
	v_fmamk_f32 v214, v74, 0x3e0293ee, v207
	v_fmamk_f32 v215, v75, 0x3e0293ee, v207
	v_fmamk_f32 v208, v76, 0x3e0293ee, v207
	v_fmamk_f32 v225, v77, 0x3e0293ee, v207
	v_fmamk_f32 v226, v78, 0x3e0293ee, v207
	v_fmac_f32_e32 v207, 0x3e0293ee, v79
	s_waitcnt lgkmcnt(0)
	s_barrier
	ds_read_b128 v[64:67], v189 offset:32768
	ds_read_b128 v[68:71], v189 offset:40960
	ds_read_b128 v[228:231], v199 offset:32768
	ds_read_b128 v[232:235], v199 offset:40960
	ds_read_b128 v[240:243], v192 offset:32768
	ds_read_b128 v[244:247], v192 offset:40960
	v_exp_f32_e32 v221, v207
	s_waitcnt lgkmcnt(4)
	v_mfma_f32_32x32x16_bf16 v[80:95], v[64:67], v[112:115], 0
	v_add_f32_e32 v207, v175, v160
	v_add_f32_e32 v207, v161, v207
	v_add_f32_e32 v207, v174, v207
	v_add_f32_e32 v207, v162, v207
	v_add_f32_e32 v207, v173, v207
	v_add_f32_e32 v207, v163, v207
	v_add_f32_e32 v207, v172, v207
	v_mfma_f32_32x32x16_bf16 v[64:79], v[68:71], v[112:115], 0
	v_add_f32_e32 v207, v164, v207
	v_add_f32_e32 v207, v171, v207
	v_add_f32_e32 v207, v165, v207
	v_add_f32_e32 v207, v170, v207
	v_exp_f32_e32 v194, v216
	v_add_f32_e32 v207, v166, v207
	v_exp_f32_e32 v195, v217
	s_waitcnt lgkmcnt(2)
	v_mfma_f32_32x32x16_bf16 v[80:95], v[228:231], v[108:111], v[80:95]
	v_add_f32_e32 v207, v169, v207
	v_exp_f32_e32 v196, v218
	v_add_f32_e32 v207, v167, v207
	v_exp_f32_e32 v197, v219
	v_add_f32_e32 v207, v168, v207
	v_exp_f32_e32 v216, v224
	v_add_f32_e32 v207, v194, v207
	v_mfma_f32_32x32x16_bf16 v[64:79], v[232:235], v[108:111], v[64:79]
	ds_read_b128 v[228:231], v191 offset:32768
	ds_read_b128 v[232:235], v191 offset:40960
	v_exp_f32_e32 v209, v209
	v_add_f32_e32 v207, v195, v207
	v_exp_f32_e32 v210, v210
	v_add_f32_e32 v207, v196, v207
	v_exp_f32_e32 v211, v211
	v_add_f32_e32 v207, v197, v207
	s_waitcnt lgkmcnt(2)
	v_mfma_f32_32x32x16_bf16 v[80:95], v[240:243], v[120:123], v[80:95]
	v_exp_f32_e32 v212, v212
	v_add_f32_e32 v207, v216, v207
	v_exp_f32_e32 v213, v213
	v_add_f32_e32 v207, v209, v207
	v_exp_f32_e32 v214, v214
	v_add_f32_e32 v207, v210, v207
	v_exp_f32_e32 v215, v215
	v_mfma_f32_32x32x16_bf16 v[64:79], v[244:247], v[120:123], v[64:79]
	ds_read_b128 v[240:243], v189 offset:32896
	ds_read_b128 v[244:247], v189 offset:41088
	v_add_f32_e32 v207, v211, v207
	v_exp_f32_e32 v217, v208
	v_add_f32_e32 v207, v212, v207
	v_exp_f32_e32 v218, v225
	v_add_f32_e32 v207, v213, v207
	v_exp_f32_e32 v219, v226
	s_waitcnt lgkmcnt(2)
	v_mfma_f32_32x32x16_bf16 v[80:95], v[228:231], v[124:127], v[80:95]
	v_add_f32_e32 v207, v214, v207
	v_add_f32_e32 v207, v215, v207
	v_add_f32_e32 v207, v217, v207
	v_add_f32_e32 v207, v218, v207
	v_add_f32_e32 v207, v219, v207
	v_add_f32_e32 v207, v221, v207
	v_mfma_f32_32x32x16_bf16 v[64:79], v[232:235], v[124:127], v[64:79]
	ds_read_b128 v[228:231], v199 offset:32896
	ds_read_b128 v[232:235], v199 offset:41088
	s_waitcnt lgkmcnt(2)
	v_mfma_f32_32x32x16_bf16 v[80:95], v[240:243], v[116:119], v[80:95]
	v_mfma_f32_32x32x16_bf16 v[64:79], v[244:247], v[116:119], v[64:79]
	ds_read_b128 v[240:243], v192 offset:32896
	ds_read_b128 v[244:247], v192 offset:41088
	s_waitcnt lgkmcnt(2)
	v_mfma_f32_32x32x16_bf16 v[80:95], v[228:231], v[104:107], v[80:95]
	v_mfma_f32_32x32x16_bf16 v[64:79], v[232:235], v[104:107], v[64:79]
	ds_read_b128 v[228:231], v191 offset:32896
	ds_read_b128 v[232:235], v191 offset:41088
	s_waitcnt lgkmcnt(2)
	v_mfma_f32_32x32x16_bf16 v[80:95], v[240:243], v[100:103], v[80:95]
	v_mfma_f32_32x32x16_bf16 v[64:79], v[244:247], v[100:103], v[64:79]
	v_cvt_pk_bf16_f32 v160, v160, v175
	v_cvt_pk_bf16_f32 v161, v161, v174
	v_cvt_pk_bf16_f32 v162, v162, v173
	v_cvt_pk_bf16_f32 v163, v163, v172
	v_cvt_pk_bf16_f32 v164, v164, v171
	v_cvt_pk_bf16_f32 v165, v165, v170
	s_waitcnt lgkmcnt(0)
	v_mfma_f32_32x32x16_bf16 v[80:95], v[228:231], v[96:99], v[80:95]
	v_cvt_pk_bf16_f32 v166, v166, v169
	v_cvt_pk_bf16_f32 v167, v167, v168
	v_cvt_pk_bf16_f32 v168, v194, v195
	v_cvt_pk_bf16_f32 v169, v196, v197
	v_cvt_pk_bf16_f32 v170, v216, v209
	v_cvt_pk_bf16_f32 v171, v210, v211
	v_cvt_pk_bf16_f32 v172, v212, v213
	v_mfma_f32_32x32x16_bf16 v[64:79], v[232:235], v[96:99], v[64:79]
	v_cvt_pk_bf16_f32 v173, v214, v215
	v_cvt_pk_bf16_f32 v174, v217, v218
	v_cvt_pk_bf16_f32 v175, v219, v221
	s_add_i32 s50, s50, 2
	s_cmp_ge_u32 s50, s49
	s_cselect_b64 s[44:45], -1, 0
	s_and_b64 vcc, exec, s[44:45]
	s_cbranch_vccnz .Lattn_skip_loads
	global_load_dwordx4 v[128:131], v183, s[52:53]
	global_load_dwordx4 v[132:135], v183, s[52:53] offset:-512
	global_load_dwordx4 v[136:139], v186, s[52:53]
	global_load_dwordx4 v[140:143], v186, s[52:53] offset:-512
	s_add_u32 s52, s52, 0x60000
	s_addc_u32 s53, s53, 0
